# NA (fixed-softmax path): LDS-DMA prefetch distance 1->2 with the same two buffers (block kb+2 issued once buf0 is read, kb+3 once buf1 is read; counted vmcnt waits)
# baseline (speedup 1.0000x reference)
.LBB0_1263:
	v_add_f32_e32 v64, 0, v148
	v_add_f32_e32 v65, 0, v177
	v_add_f32_e32 v64, v64, v179
	v_add_f32_e32 v65, v65, v202
	v_add_f32_e32 v64, v64, v203
	v_add_f32_e32 v65, v65, v204
	v_add_f32_e32 v148, v64, v205
	v_add_f32_e32 v64, v65, v230
	v_mov_b32_e32 v65, v149
	v_pk_add_f32 v[66:67], v[148:149], v[74:75]
	v_pk_add_f32 v[64:65], v[64:65], v[72:73]
	v_pk_add_f32 v[66:67], v[66:67], v[68:69]
	v_pk_add_f32 v[64:65], v[64:65], v[70:71]
	v_pk_add_f32 v[66:67], v[66:67], v[78:79]
	v_pk_add_f32 v[64:65], v[64:65], v[198:199]
	v_pk_add_f32 v[66:67], v[66:67], v[76:77]
	v_pk_add_f32 v[64:65], v[64:65], v[200:201]
	v_readlane_b32 s14, v254, 41
	v_pk_add_f32 v[64:65], v[66:67], v[64:65]
	v_readlane_b32 s15, v254, 42
	v_pk_add_f32 v[190:191], v[190:191], v[64:65]
	v_mfma_f32_32x32x16_bf16 v[64:79], v[140:143], v[96:99], 0
	s_add_i32 s12, s12, 2
	v_lshl_add_u64 v[188:189], v[188:189], 0, s[28:29]
	v_add_u32_e32 v228, 0x7c, v228
	v_add_u32_e32 v229, 0x7c, v229
	s_andn2_b64 vcc, exec, s[8:9]
	s_waitcnt lgkmcnt(0)
	s_cbranch_vccz .Lna_skip_b
	s_mov_b64 s[98:99], 0x17618000
	s_add_i32 m0, s33, 0x2000
	v_lshl_add_u64 v[152:153], v[192:193], 0, s[98:99]
	global_load_lds_dwordx4 v[152:153], off
	s_mov_b64 s[98:99], 0x17619000
	s_add_i32 m0, s33, 0x2400
	v_lshl_add_u64 v[208:209], v[194:195], 0, s[98:99]
	global_load_lds_dwordx4 v[208:209], off
	s_mov_b64 s[98:99], 0x1761c000
	s_add_i32 m0, s33, 0x2800
	v_lshl_add_u64 v[152:153], v[192:193], 0, s[98:99]
	global_load_lds_dwordx4 v[152:153], off
	s_mov_b64 s[98:99], 0x1761d000
	s_add_i32 m0, s33, 0x2c00
	v_lshl_add_u64 v[208:209], v[194:195], 0, s[98:99]
	global_load_lds_dwordx4 v[208:209], off
	s_mov_b64 s[98:99], 0x196000c0
	s_add_i32 m0, s33, 0x3000
	v_lshl_add_u64 v[152:153], v[196:197], 0, s[98:99]
	global_load_lds_dwordx4 v[152:153], off
	s_mov_b64 s[98:99], 0x197000c0
	s_add_i32 m0, s33, 0x3400
	v_lshl_add_u64 v[208:209], v[196:197], 0, s[98:99]
	global_load_lds_dwordx4 v[208:209], off
	s_mov_b64 s[98:99], 0x198000c0
	s_add_i32 m0, s33, 0x3800
	v_lshl_add_u64 v[152:153], v[196:197], 0, s[98:99]
	global_load_lds_dwordx4 v[152:153], off
	s_mov_b64 s[98:99], 0x199000c0
	s_add_i32 m0, s33, 0x3c00
	v_lshl_add_u64 v[208:209], v[196:197], 0, s[98:99]
	global_load_lds_dwordx4 v[208:209], off
.Lna_skip_b:
	v_mfma_f32_32x32x16_bf16 v[64:79], v[136:139], v[100:103], v[64:79]
	v_mfma_f32_32x32x16_bf16 v[64:79], v[128:131], v[104:107], v[64:79]
	v_mfma_f32_32x32x16_bf16 v[64:79], v[132:135], v[108:111], v[64:79]
	s_nop 11
	v_add_u32_e32 v71, 0x20330, v175
	ds_read2_b32 v[72:73], v71 offset1:1
	s_waitcnt lgkmcnt(0)
	v_add_f32_e32 v64, v64, v72
	v_cndmask_b32_e64 v71, v216, v64, s[60:61]
	v_add_f32_e32 v64, v65, v73
	v_cndmask_b32_e64 v72, v216, v64, s[62:63]
	v_add_u32_e32 v64, 0x20338, v175
	ds_read2_b32 v[64:65], v64 offset1:1
	v_exp_f32_e32 v194, v71
	v_exp_f32_e32 v192, v72
	s_waitcnt lgkmcnt(0)
	v_add_f32_e32 v64, v66, v64
	v_cndmask_b32_e64 v66, v216, v64, s[64:65]
	v_add_f32_e32 v64, v67, v65
	v_cndmask_b32_e64 v67, v216, v64, s[66:67]
	v_add_u32_e32 v64, 0x20340, v175
	ds_read2_b32 v[64:65], v64 offset1:1
	v_exp_f32_e32 v198, v66
	v_exp_f32_e32 v196, v67
	s_waitcnt lgkmcnt(0)
	v_add_f32_e32 v64, v68, v64
	v_add_u32_e32 v68, 0x20348, v175
	ds_read_b32 v68, v68
	v_add_f32_e32 v65, v69, v65
	v_cndmask_b32_e64 v64, v216, v64, s[68:69]
	v_cndmask_b32_e64 v65, v216, v65, s[70:71]
	v_exp_f32_e32 v202, v64
	s_waitcnt lgkmcnt(0)
	v_add_f32_e32 v68, v70, v68
	v_cndmask_b32_e64 v68, v216, v68, s[72:73]
	v_exp_f32_e32 v200, v65
	v_exp_f32_e32 v204, v68
	v_mfma_f32_32x32x16_bf16 v[64:79], v[140:143], v[112:115], 0
	v_mfma_f32_32x32x16_bf16 v[64:79], v[136:139], v[116:119], v[64:79]
	v_mfma_f32_32x32x16_bf16 v[64:79], v[128:131], v[120:123], v[64:79]
	v_add_u32_e32 v128, 0x20330, v159
	ds_read2_b32 v[128:129], v128 offset1:1
	v_mfma_f32_32x32x16_bf16 v[64:79], v[132:135], v[124:127], v[64:79]
	s_waitcnt lgkmcnt(0)
	s_nop 10
	v_add_f32_e32 v64, v64, v128
	v_cndmask_b32_e64 v128, v216, v64, s[14:15]
	v_add_f32_e32 v64, v65, v129
	v_cndmask_b32_e64 v129, v216, v64, s[74:75]
	v_add_u32_e32 v64, 0x20338, v159
	ds_read2_b32 v[64:65], v64 offset1:1
	s_mov_b64 s[14:15], 0x10000
	v_lshl_add_u64 v[184:185], v[184:185], 0, s[14:15]
	v_lshl_add_u64 v[186:187], v[186:187], 0, s[14:15]
	s_waitcnt lgkmcnt(0)
	v_add_f32_e32 v64, v66, v64
	v_cndmask_b32_e64 v66, v216, v64, s[76:77]
	v_add_f32_e32 v64, v67, v65
	v_cndmask_b32_e64 v67, v216, v64, s[78:79]
	v_add_u32_e32 v64, 0x20340, v159
	ds_read2_b32 v[64:65], v64 offset1:1
	v_exp_f32_e32 v130, v66
	v_exp_f32_e32 v131, v67
	s_waitcnt lgkmcnt(0)
	v_add_f32_e32 v64, v68, v64
	v_cndmask_b32_e64 v68, v216, v64, s[80:81]
	v_add_f32_e32 v64, v69, v65
	v_cndmask_b32_e64 v69, v216, v64, s[82:83]
	v_add_u32_e32 v64, 0x20348, v159
	ds_read2_b32 v[64:65], v64 offset1:1
	s_waitcnt lgkmcnt(0)
	v_add_f32_e32 v64, v70, v64
	v_cndmask_b32_e64 v70, v216, v64, s[84:85]
	v_add_f32_e32 v64, v71, v65
	v_cndmask_b32_e64 v71, v216, v64, s[86:87]
	v_add_u32_e32 v64, 0x20370, v159
	ds_read2_b32 v[64:65], v64 offset1:1
	v_exp_f32_e32 v132, v70
	v_exp_f32_e32 v133, v71
	v_mov_b32_e32 v70, v149
	s_waitcnt lgkmcnt(0)
	v_add_f32_e32 v64, v72, v64
	v_cndmask_b32_e64 v72, v216, v64, s[88:89]
	v_add_f32_e32 v64, v73, v65
	v_cndmask_b32_e64 v73, v216, v64, s[90:91]
	v_add_u32_e32 v64, 0x20378, v159
	ds_read2_b32 v[64:65], v64 offset1:1
	v_exp_f32_e32 v72, v72
	v_exp_f32_e32 v195, v73
	s_waitcnt lgkmcnt(0)
	v_add_f32_e32 v64, v74, v64
	v_cndmask_b32_e64 v74, v216, v64, s[92:93]
	v_add_f32_e32 v64, v75, v65
	v_cndmask_b32_e64 v75, v216, v64, s[94:95]
	v_add_u32_e32 v64, 0x20380, v159
	ds_read2_b32 v[64:65], v64 offset1:1
	v_exp_f32_e32 v193, v74
	v_exp_f32_e32 v199, v75
	s_waitcnt lgkmcnt(0)
	v_add_f32_e32 v64, v76, v64
	v_cndmask_b32_e64 v76, v216, v64, s[96:97]
	v_add_f32_e32 v64, v77, v65
	v_cndmask_b32_e64 v77, v216, v64, s[2:3]
	v_add_u32_e32 v64, 0x20388, v159
	ds_read2_b32 v[64:65], v64 offset1:1
	v_exp_f32_e32 v197, v76
	v_exp_f32_e32 v203, v77
	s_waitcnt lgkmcnt(0)
	v_add_f32_e32 v64, v78, v64
	v_exp_f32_e32 v78, v128
	v_add_f32_e32 v65, v79, v65
	v_exp_f32_e32 v79, v129
	v_cndmask_b32_e64 v64, v216, v64, s[4:5]
	v_add_f32_e32 v128, 0, v78
	v_add_f32_e32 v66, v128, v130
	v_add_f32_e32 v129, 0, v79
	v_exp_f32_e32 v128, v68
	v_add_f32_e32 v67, v129, v131
	v_exp_f32_e32 v129, v69
	v_cndmask_b32_e64 v65, v216, v65, s[0:1]
	v_add_f32_e32 v66, v66, v128
	v_add_f32_e32 v66, v66, v132
	v_add_f32_e32 v67, v67, v129
	v_add_f32_e32 v69, v67, v133
	v_add_f32_e32 v71, v66, v72
	v_exp_f32_e32 v201, v64
	v_exp_f32_e32 v205, v65
	v_cvt_pk_bf16_f32 v64, v194, v192
	v_cvt_pk_bf16_f32 v65, v198, v196
	v_cvt_pk_bf16_f32 v66, v202, v200
	v_cvt_pk_bf16_f32 v67, v204, 0
	v_mov_b32_e32 v68, v149
	v_pk_add_f32 v[68:69], v[68:69], v[194:195]
	v_mfma_f32_32x32x16_bf16 v[32:47], v[92:95], v[64:67], v[32:47]
	v_add_f32_e64 v70, v70, v192
	v_add_f32_e64 v71, v71, v193
	v_add_f32_e64 v68, v68, v198
	v_add_f32_e64 v69, v69, v199
	v_add_f32_e64 v70, v70, v196
	v_add_f32_e64 v71, v71, v197
	v_pk_add_f32 v[68:69], v[68:69], v[202:203]
	v_pk_add_f32 v[70:71], v[70:71], v[200:201]
	v_pk_add_f32 v[68:69], v[68:69], v[204:205]
	v_mfma_f32_32x32x16_bf16 v[48:63], v[88:91], v[64:67], v[48:63]
	v_cvt_pk_bf16_f32 v64, v78, v79
	v_cvt_pk_bf16_f32 v65, v130, v131
	v_cvt_pk_bf16_f32 v66, v128, v129
	v_cvt_pk_bf16_f32 v67, v132, v133
	v_add_f32_e64 v68, v70, v68
	v_add_f32_e64 v69, v71, v69
	v_pk_add_f32 v[190:191], v[190:191], v[68:69]
	v_mfma_f32_32x32x16_bf16 v[0:15], v[92:95], v[64:67], v[0:15]
	v_mfma_f32_32x32x16_bf16 v[16:31], v[88:91], v[64:67], v[16:31]
	v_cvt_pk_bf16_f32 v64, v72, v195
	v_cvt_pk_bf16_f32 v65, v193, v199
	v_cvt_pk_bf16_f32 v66, v197, v203
	v_cvt_pk_bf16_f32 v67, v201, v205
	s_nop 1
	v_mfma_f32_32x32x16_bf16 v[0:15], v[84:87], v[64:67], v[0:15]
	v_mfma_f32_32x32x16_bf16 v[16:31], v[80:83], v[64:67], v[16:31]
	s_cbranch_vccz .LBB0_1253
.LBB0_1264:
	v_lshl_add_u64 v[192:193], v[184:185], 0, s[10:11]
	v_lshl_add_u64 v[194:195], v[186:187], 0, s[10:11]
	v_lshl_add_u64 v[196:197], v[188:189], 0, s[10:11]
	s_cmp_lg_u32 s12, 0
	s_cbranch_scc1 .Lna_top_steady
	s_waitcnt vmcnt(0)
	s_mov_b64 s[98:99], 0x17608000
	s_add_i32 m0, s33, 0x2000
	v_lshl_add_u64 v[152:153], v[192:193], 0, s[98:99]
	global_load_lds_dwordx4 v[152:153], off
	s_mov_b64 s[98:99], 0x17609000
	s_add_i32 m0, s33, 0x2400
	v_lshl_add_u64 v[208:209], v[194:195], 0, s[98:99]
	global_load_lds_dwordx4 v[208:209], off
	s_mov_b64 s[98:99], 0x1760c000
	s_add_i32 m0, s33, 0x2800
	v_lshl_add_u64 v[152:153], v[192:193], 0, s[98:99]
	global_load_lds_dwordx4 v[152:153], off
	s_mov_b64 s[98:99], 0x1760d000
	s_add_i32 m0, s33, 0x2c00
	v_lshl_add_u64 v[208:209], v[194:195], 0, s[98:99]
	global_load_lds_dwordx4 v[208:209], off
	s_mov_b64 s[98:99], 0x19600040
	s_add_i32 m0, s33, 0x3000
	v_lshl_add_u64 v[152:153], v[196:197], 0, s[98:99]
	global_load_lds_dwordx4 v[152:153], off
	s_mov_b64 s[98:99], 0x19700040
	s_add_i32 m0, s33, 0x3400
	v_lshl_add_u64 v[208:209], v[196:197], 0, s[98:99]
	global_load_lds_dwordx4 v[208:209], off
	s_mov_b64 s[98:99], 0x19800040
	s_add_i32 m0, s33, 0x3800
	v_lshl_add_u64 v[152:153], v[196:197], 0, s[98:99]
	global_load_lds_dwordx4 v[152:153], off
	s_mov_b64 s[98:99], 0x19900040
	s_add_i32 m0, s33, 0x3c00
	v_lshl_add_u64 v[208:209], v[196:197], 0, s[98:99]
	global_load_lds_dwordx4 v[208:209], off
	s_branch .Lna_top_join
.Lna_top_steady:
	s_waitcnt vmcnt(8)
.Lna_top_join:
	ds_read_b128 v[80:83], v222
	ds_read_b128 v[136:139], v223
	ds_read_b128 v[132:135], v224
	ds_read_b128 v[128:131], v225
	ds_read_b128 v[84:87], v226 offset:4096
	s_waitcnt lgkmcnt(0)
	v_mfma_f32_32x32x16_bf16 v[64:79], v[80:83], v[96:99], 0
	v_mfma_f32_32x32x16_bf16 v[64:79], v[136:139], v[100:103], v[64:79]
	v_mfma_f32_32x32x16_bf16 v[64:79], v[132:135], v[104:107], v[64:79]
	v_mfma_f32_32x32x16_bf16 v[64:79], v[128:131], v[108:111], v[64:79]
	v_add_u32_e32 v175, v229, v163
	v_add_u32_e32 v88, 0x202b0, v175
	ds_read2_b32 v[88:89], v88 offset1:1
	v_add_u32_e32 v90, 0x202b8, v175
	ds_read2_b32 v[90:91], v90 offset1:1
	v_readlane_b32 s8, v254, 45
	v_readlane_b32 s9, v254, 46
	s_waitcnt lgkmcnt(0)
	s_nop 4
	v_add_f32_e32 v64, v64, v88
	v_add_u32_e32 v159, v228, v163
	v_cndmask_b32_e64 v88, v216, v64, s[8:9]
	v_readlane_b32 s8, v254, 47
	v_add_f32_e32 v64, v65, v89
	v_readlane_b32 s9, v254, 48
	v_exp_f32_e32 v148, v88
	s_cmp_gt_u32 s12, 13
	v_cndmask_b32_e64 v89, v216, v64, s[8:9]
	v_readlane_b32 s8, v254, 49
	v_add_f32_e32 v64, v66, v90
	v_readlane_b32 s9, v254, 50
	v_add_f32_e32 v66, v67, v91
	v_exp_f32_e32 v177, v89
	v_cndmask_b32_e64 v90, v216, v64, s[8:9]
	v_readlane_b32 s8, v254, 51
	v_readlane_b32 s9, v254, 52
	v_add_u32_e32 v64, 0x202c0, v175
	ds_read2_b32 v[64:65], v64 offset1:1
	v_cndmask_b32_e64 v91, v216, v66, s[8:9]
	v_add_u32_e32 v66, 0x202c8, v175
	ds_read2_b32 v[66:67], v66 offset1:1
	v_exp_f32_e32 v179, v90
	s_waitcnt lgkmcnt(0)
	v_add_f32_e32 v64, v68, v64
	v_add_f32_e32 v65, v69, v65
	v_cndmask_b32_e64 v64, v216, v64, s[20:21]
	v_add_f32_e32 v66, v70, v66
	v_add_f32_e32 v67, v71, v67
	v_cndmask_b32_e64 v65, v216, v65, s[22:23]
	v_cndmask_b32_e64 v66, v216, v66, s[24:25]
	v_cndmask_b32_e64 v67, v216, v67, s[26:27]
	v_exp_f32_e32 v202, v91
	v_exp_f32_e32 v203, v64
	v_exp_f32_e32 v204, v65
	v_exp_f32_e32 v205, v66
	v_exp_f32_e32 v230, v67
	v_cvt_pk_bf16_f32 v140, v148, v177
	v_cvt_pk_bf16_f32 v141, v179, v202
	v_cvt_pk_bf16_f32 v142, v203, v204
	v_cvt_pk_bf16_f32 v143, v205, v230
	v_add_u32_e32 v68, 0x202f0, v175
	ds_read2_b32 v[68:69], v68 offset1:1
	v_mfma_f32_32x32x16_bf16 v[32:47], v[84:87], v[140:143], v[32:47]
	v_add_u32_e32 v70, 0x202f8, v175
	ds_read_b128 v[154:157], v226 offset:6144
	ds_read_b128 v[64:67], v227 offset:4096
	ds_read_b128 v[212:215], v227 offset:6144
	ds_read2_b32 v[70:71], v70 offset1:1
	s_waitcnt lgkmcnt(0)
	s_cbranch_scc1 .Lna_skip_a
	s_mov_b64 s[98:99], 0x17610000
	s_add_i32 m0, s33, 0x0
	v_lshl_add_u64 v[152:153], v[192:193], 0, s[98:99]
	global_load_lds_dwordx4 v[152:153], off
	s_mov_b64 s[98:99], 0x17611000
	s_add_i32 m0, s33, 0x400
	v_lshl_add_u64 v[208:209], v[194:195], 0, s[98:99]
	global_load_lds_dwordx4 v[208:209], off
	s_mov_b64 s[98:99], 0x17614000
	s_add_i32 m0, s33, 0x800
	v_lshl_add_u64 v[152:153], v[192:193], 0, s[98:99]
	global_load_lds_dwordx4 v[152:153], off
	s_mov_b64 s[98:99], 0x17615000
	s_add_i32 m0, s33, 0xc00
	v_lshl_add_u64 v[208:209], v[194:195], 0, s[98:99]
	global_load_lds_dwordx4 v[208:209], off
	s_mov_b64 s[98:99], 0x19600080
	s_add_i32 m0, s33, 0x1000
	v_lshl_add_u64 v[152:153], v[196:197], 0, s[98:99]
	global_load_lds_dwordx4 v[152:153], off
	s_mov_b64 s[98:99], 0x19700080
	s_add_i32 m0, s33, 0x1400
	v_lshl_add_u64 v[208:209], v[196:197], 0, s[98:99]
	global_load_lds_dwordx4 v[208:209], off
	s_mov_b64 s[98:99], 0x19800080
	s_add_i32 m0, s33, 0x1800
	v_lshl_add_u64 v[152:153], v[196:197], 0, s[98:99]
	global_load_lds_dwordx4 v[152:153], off
	s_mov_b64 s[98:99], 0x19900080
	s_add_i32 m0, s33, 0x1c00
	v_lshl_add_u64 v[208:209], v[196:197], 0, s[98:99]
	global_load_lds_dwordx4 v[208:209], off
.Lna_skip_a:
	s_cmp_gt_u32 s12, 13
	v_add_f32_e32 v68, v72, v68
	v_cndmask_b32_e64 v72, v216, v68, s[6:7]
	v_add_f32_e32 v68, v73, v69
	v_cndmask_b32_e64 v73, v216, v68, s[30:31]
	v_mfma_f32_32x32x16_bf16 v[80:95], v[80:83], v[112:115], 0
	v_add_f32_e32 v68, v74, v70
	v_cndmask_b32_e64 v150, v216, v68, s[34:35]
	v_add_u32_e32 v68, 0x20300, v175
	ds_read2_b32 v[68:69], v68 offset1:1
	v_add_f32_e32 v70, v75, v71
	v_cndmask_b32_e64 v75, v216, v70, s[36:37]
	v_add_u32_e32 v70, 0x20308, v175
	v_mfma_f32_32x32x16_bf16 v[80:95], v[136:139], v[116:119], v[80:95]
	s_waitcnt lgkmcnt(0)
	v_add_f32_e32 v68, v76, v68
	v_cndmask_b32_e64 v76, v216, v68, s[38:39]
	v_add_f32_e32 v68, v77, v69
	v_cndmask_b32_e64 v69, v216, v68, s[40:41]
	v_exp_f32_e32 v198, v69
	v_add_u32_e32 v69, 0x202f0, v159
	ds_read2_b32 v[70:71], v70 offset1:1
	v_mfma_f32_32x32x16_bf16 v[80:95], v[132:135], v[120:123], v[80:95]
	v_exp_f32_e32 v74, v72
	v_exp_f32_e32 v72, v73
	v_readlane_b32 s8, v254, 43
	s_waitcnt lgkmcnt(0)
	v_add_f32_e32 v68, v78, v70
	v_cndmask_b32_e64 v77, v216, v68, s[42:43]
	v_add_f32_e32 v68, v79, v71
	v_cndmask_b32_e64 v71, v216, v68, s[44:45]
	v_mfma_f32_32x32x16_bf16 v[80:95], v[128:131], v[124:127], v[80:95]
	v_exp_f32_e32 v78, v76
	v_exp_f32_e32 v76, v77
	v_exp_f32_e32 v200, v71
	v_readlane_b32 s9, v254, 44
	v_exp_f32_e32 v68, v150
	s_nop 6
	ds_read2_b32 v[80:81], v69 offset1:1
	v_add_u32_e32 v69, 0x202f8, v159
	ds_read2_b32 v[82:83], v69 offset1:1
	v_exp_f32_e32 v70, v75
	v_mfma_f32_32x32x16_bf16 v[48:63], v[154:157], v[140:143], v[48:63]
	s_waitcnt lgkmcnt(0)
	v_add_f32_e32 v69, v88, v80
	v_add_f32_e32 v71, v89, v81
	v_add_f32_e32 v73, v90, v82
	v_cndmask_b32_e64 v77, v216, v73, s[48:49]
	v_add_u32_e32 v73, 0x20300, v159
	ds_read2_b32 v[80:81], v73 offset1:1
	v_add_f32_e32 v73, v91, v83
	v_cndmask_b32_e64 v79, v216, v73, s[50:51]
	v_add_u32_e32 v73, 0x20308, v159
	ds_read2_b32 v[82:83], v73 offset1:1
	s_waitcnt lgkmcnt(0)
	v_add_f32_e32 v73, v92, v80
	v_cndmask_b32_e64 v80, v216, v73, s[52:53]
	v_add_f32_e32 v73, v93, v81
	v_cndmask_b32_e64 v84, v216, v73, s[54:55]
	v_add_f32_e32 v73, v94, v82
	v_cndmask_b32_e64 v85, v216, v73, s[56:57]
	v_add_f32_e32 v73, v95, v83
	v_cndmask_b32_e64 v69, v216, v69, s[8:9]
	v_cndmask_b32_e64 v71, v216, v71, s[46:47]
	v_cndmask_b32_e64 v86, v216, v73, s[58:59]
	v_exp_f32_e32 v75, v69
	v_exp_f32_e32 v73, v71
	v_exp_f32_e32 v69, v77
	v_exp_f32_e32 v71, v79
	v_exp_f32_e32 v79, v80
	v_exp_f32_e32 v199, v84
	v_exp_f32_e32 v77, v85
	v_exp_f32_e32 v201, v86
	v_cvt_pk_bf16_f32 v80, v74, v72
	v_cvt_pk_bf16_f32 v81, v68, v70
	v_cvt_pk_bf16_f32 v82, v78, v198
	v_cvt_pk_bf16_f32 v83, v76, v200
	v_cvt_pk_bf16_f32 v154, v75, v73
	v_cvt_pk_bf16_f32 v155, v69, v71
	v_cvt_pk_bf16_f32 v156, v79, v199
	v_cvt_pk_bf16_f32 v157, v77, v201
	v_mfma_f32_32x32x16_bf16 v[32:47], v[64:67], v[80:83], v[32:47]
	s_cselect_b64 s[8:9], -1, 0
	s_and_b64 vcc, exec, s[8:9]
	v_mfma_f32_32x32x16_bf16 v[0:15], v[64:67], v[154:157], v[0:15]
	s_cbranch_vccnz .Lna_mid_w0
	s_waitcnt vmcnt(8)
	s_branch .Lna_mid_wj

.Lna_mid_wj:
	ds_read_b128 v[140:143], v222 offset:8192
	s_waitcnt lgkmcnt(0)
	v_mfma_f32_32x32x16_bf16 v[48:63], v[212:215], v[80:83], v[48:63]
	ds_read_b128 v[136:139], v223 offset:8192
	ds_read_b128 v[128:131], v224 offset:8192
	ds_read_b128 v[132:135], v225 offset:8192
	ds_read_b128 v[92:95], v226 offset:12288
	ds_read_b128 v[88:91], v226 offset:14336
	ds_read_b128 v[84:87], v227 offset:12288
	ds_read_b128 v[80:83], v227 offset:14336
	v_mfma_f32_32x32x16_bf16 v[16:31], v[212:215], v[154:157], v[16:31]
	s_branch .LBB0_1263
